# attention unit epilogue: pairs of 8-byte row stores merged into 16-byte stores via v_permlane16_swap (same bytes, same addresses)
# speedup vs baseline: 1.0013x; 1.0013x over previous
.Lqe3:
	v_mov_b32_e32 v4, v101
	s_nop 1
	v_permlane16_swap_b32_e32 v101, v4
	v_add_f32_e32 v4, v101, v4
	v_mov_b32_e32 v5, v4
	s_nop 1
	v_permlane32_swap_b32_e32 v4, v5
	v_add_f32_e32 v4, v4, v5
	v_div_scale_f32 v5, s[6:7], v4, v4, 1.0
	v_rcp_f32_e32 v6, v5
	v_lshlrev_b32_e32 v88, 1, v97
	v_fma_f32 v7, -v5, v6, 1.0
	v_fmac_f32_e32 v6, v7, v6
	v_div_scale_f32 v7, vcc, 1.0, v4, 1.0
	v_mul_f32_e32 v8, v7, v6
	v_fma_f32 v9, -v5, v8, v7
	v_fmac_f32_e32 v8, v9, v6
	v_fma_f32 v5, -v5, v8, v7
	v_div_fmas_f32 v5, v5, v6, v8
	v_lshlrev_b64 v[6:7], 11, v[92:93]
	v_div_fixup_f32 v4, v5, v4, 1.0
	v_lshl_add_u64 v[6:7], s[48:49], 0, v[6:7]
	v_lshl_add_u64 v[6:7], v[6:7], 0, s[44:45]
	v_pk_mul_f32 v[8:9], v[68:69], v[4:5] op_sel_hi:[1,0]
	v_pk_mul_f32 v[10:11], v[70:71], v[4:5] op_sel_hi:[1,0]
	v_lshl_add_u64 v[6:7], v[6:7], 0, v[88:89]
	v_cvt_pk_bf16_f32 v44, v8, v9
	v_cvt_pk_bf16_f32 v45, v10, v11
	s_nop 0
	v_pk_mul_f32 v[8:9], v[64:65], v[4:5] op_sel_hi:[1,0]
	v_pk_mul_f32 v[10:11], v[66:67], v[4:5] op_sel_hi:[1,0]
	v_cvt_pk_bf16_f32 v46, v8, v9
	v_cvt_pk_bf16_f32 v47, v10, v11
	v_mbcnt_lo_u32_b32 v108, -1, 0
	v_mbcnt_hi_u32_b32 v108, -1, v108
	v_and_b32_e32 v108, 16, v108
	v_lshrrev_b32_e32 v108, 1, v108
	v_mul_u32_u24_e32 v108, 3, v108
	v_mov_b32_e32 v109, 0
	v_lshl_add_u64 v[110:111], v[6:7], 0, v[108:109]
	s_nop 1
	v_permlane16_swap_b32_e32 v44, v46
	v_permlane16_swap_b32_e32 v45, v47
	flat_store_dwordx4 v[110:111], v[44:47]
	v_pk_mul_f32 v[8:9], v[72:73], v[4:5] op_sel_hi:[1,0]
	v_pk_mul_f32 v[10:11], v[74:75], v[4:5] op_sel_hi:[1,0]
	v_cvt_pk_bf16_f32 v80, v8, v9
	v_cvt_pk_bf16_f32 v81, v10, v11
	s_nop 0
	v_pk_mul_f32 v[8:9], v[76:77], v[4:5] op_sel_hi:[1,0]
	v_mov_b32_e32 v5, v100
	s_nop 1
	v_permlane16_swap_b32_e32 v100, v5
	v_add_f32_e32 v5, v100, v5
	v_cvt_pk_bf16_f32 v82, v8, v9
	v_mov_b32_e32 v9, v5
	s_nop 1
	v_permlane32_swap_b32_e32 v5, v9
	v_add_f32_e32 v10, v5, v9
	v_div_scale_f32 v11, s[6:7], v10, v10, 1.0
	v_rcp_f32_e32 v12, v11
	v_pk_mul_f32 v[4:5], v[78:79], v[4:5] op_sel_hi:[1,0]
	s_nop 0
	v_cvt_pk_bf16_f32 v83, v4, v5
	v_fma_f32 v4, -v11, v12, 1.0
	v_fmac_f32_e32 v12, v4, v12
	v_div_scale_f32 v4, vcc, 1.0, v10, 1.0
	v_mul_f32_e32 v5, v4, v12
	v_lshl_add_u64 v[110:111], v[6:7], 0, v[108:109]
	s_nop 1
	v_permlane16_swap_b32_e32 v80, v82
	v_permlane16_swap_b32_e32 v81, v83
	flat_store_dwordx4 v[110:111], v[80:83] offset:64
	v_fma_f32 v6, -v11, v5, v4
	v_fmac_f32_e32 v5, v6, v12
	v_fma_f32 v4, -v11, v5, v4
	v_div_fmas_f32 v4, v4, v12, v5
	v_lshlrev_b64 v[6:7], 11, v[90:91]
	v_div_fixup_f32 v4, v4, v10, 1.0
	v_lshl_add_u64 v[6:7], s[48:49], 0, v[6:7]
	v_lshl_add_u64 v[6:7], v[6:7], 0, s[44:45]
	v_pk_mul_f32 v[8:9], v[52:53], v[4:5] op_sel_hi:[1,0]
	v_pk_mul_f32 v[10:11], v[54:55], v[4:5] op_sel_hi:[1,0]
	v_lshl_add_u64 v[6:7], v[6:7], 0, v[88:89]
	v_cvt_pk_bf16_f32 v84, v8, v9
	v_cvt_pk_bf16_f32 v85, v10, v11
	s_nop 0
	v_pk_mul_f32 v[8:9], v[48:49], v[4:5] op_sel_hi:[1,0]
	v_pk_mul_f32 v[10:11], v[50:51], v[4:5] op_sel_hi:[1,0]
	v_cvt_pk_bf16_f32 v86, v8, v9
	v_cvt_pk_bf16_f32 v87, v10, v11
	v_lshl_add_u64 v[110:111], v[6:7], 0, v[108:109]
	s_nop 1
	v_permlane16_swap_b32_e32 v84, v86
	v_permlane16_swap_b32_e32 v85, v87
	flat_store_dwordx4 v[110:111], v[84:87]
	v_pk_mul_f32 v[8:9], v[56:57], v[4:5] op_sel_hi:[1,0]
	v_pk_mul_f32 v[10:11], v[58:59], v[4:5] op_sel_hi:[1,0]
	v_cvt_pk_bf16_f32 v104, v8, v9
	v_cvt_pk_bf16_f32 v105, v10, v11
	s_nop 0
	v_pk_mul_f32 v[8:9], v[60:61], v[4:5] op_sel_hi:[1,0]
	v_pk_mul_f32 v[4:5], v[62:63], v[4:5] op_sel_hi:[1,0]
	v_cvt_pk_bf16_f32 v106, v8, v9
	v_cvt_pk_bf16_f32 v107, v4, v5
	v_lshl_add_u64 v[110:111], v[6:7], 0, v[108:109]
	s_nop 1
	v_permlane16_swap_b32_e32 v104, v106
	v_permlane16_swap_b32_e32 v105, v107
	flat_store_dwordx4 v[110:111], v[104:107] offset:64
	s_waitcnt lgkmcnt(0)
	s_barrier
	s_and_saveexec_b64 s[6:7], s[4:5]
	s_cbranch_execz .LBB0_1198
	s_cmp_eq_u32 s32, 0
	s_cbranch_scc1 .Lqf0
	s_waitcnt vmcnt(0) lgkmcnt(0)
	ds_write_b32 v178, v253
	s_mov_b32 s32, 0
	s_branch .LBB0_1198

.LBB0_1312:
	v_mov_b32_e32 v4, v97
	s_nop 1
	v_permlane16_swap_b32_e32 v97, v4
	v_add_f32_e32 v4, v97, v4
	v_mov_b32_e32 v5, v4
	s_nop 1
	v_permlane32_swap_b32_e32 v4, v5
	v_add_f32_e32 v4, v4, v5
	v_div_scale_f32 v5, s[6:7], v4, v4, 1.0
	v_rcp_f32_e32 v6, v5
	v_mov_b32_e32 v103, v89
	s_lshl_b32 s44, s94, 1
	s_mov_b64 s[8:9], 0x4552200
	v_fma_f32 v7, -v5, v6, 1.0
	v_fmac_f32_e32 v6, v7, v6
	v_div_scale_f32 v7, vcc, 1.0, v4, 1.0
	v_mul_f32_e32 v8, v7, v6
	v_fma_f32 v9, -v5, v8, v7
	v_fmac_f32_e32 v8, v9, v6
	v_fma_f32 v5, -v5, v8, v7
	v_div_fmas_f32 v5, v5, v6, v8
	v_lshlrev_b64 v[6:7], 11, v[92:93]
	v_lshl_add_u64 v[6:7], s[42:43], 0, v[6:7]
	v_lshl_add_u64 v[6:7], v[6:7], 0, s[44:45]
	v_lshlrev_b64 v[8:9], 1, v[102:103]
	v_div_fixup_f32 v4, v5, v4, 1.0
	v_lshl_add_u64 v[6:7], v[6:7], 0, v[8:9]
	s_mov_b32 s2, 0x4552000
	v_lshl_add_u64 v[10:11], v[6:7], 0, s[8:9]
	v_pk_mul_f32 v[12:13], v[56:57], v[4:5] op_sel_hi:[1,0]
	v_pk_mul_f32 v[14:15], v[58:59], v[4:5] op_sel_hi:[1,0]
	v_add_co_u32_e32 v6, vcc, s2, v6
	v_cvt_pk_bf16_f32 v72, v12, v13
	v_cvt_pk_bf16_f32 v73, v14, v15
	v_addc_co_u32_e32 v7, vcc, 0, v7, vcc
	s_nop 0
	v_pk_mul_f32 v[6:7], v[52:53], v[4:5] op_sel_hi:[1,0]
	v_pk_mul_f32 v[12:13], v[54:55], v[4:5] op_sel_hi:[1,0]
	v_cvt_pk_bf16_f32 v74, v6, v7
	v_cvt_pk_bf16_f32 v75, v12, v13
	v_mbcnt_lo_u32_b32 v104, -1, 0
	v_mbcnt_hi_u32_b32 v104, -1, v104
	v_and_b32_e32 v104, 16, v104
	v_lshrrev_b32_e32 v104, 1, v104
	v_mul_u32_u24_e32 v104, 3, v104
	v_mov_b32_e32 v105, 0
	v_lshl_add_u64 v[106:107], v[10:11], 0, v[104:105]
	s_nop 1
	v_permlane16_swap_b32_e32 v72, v74
	v_permlane16_swap_b32_e32 v73, v75
	flat_store_dwordx4 v[106:107], v[72:75]
	v_pk_mul_f32 v[6:7], v[60:61], v[4:5] op_sel_hi:[1,0]
	v_pk_mul_f32 v[12:13], v[62:63], v[4:5] op_sel_hi:[1,0]
	v_cvt_pk_bf16_f32 v76, v6, v7
	v_cvt_pk_bf16_f32 v77, v12, v13
	s_nop 0
	v_pk_mul_f32 v[6:7], v[64:65], v[4:5] op_sel_hi:[1,0]
	v_mov_b32_e32 v5, v96
	s_nop 1
	v_permlane16_swap_b32_e32 v96, v5
	v_add_f32_e32 v5, v96, v5
	v_cvt_pk_bf16_f32 v78, v6, v7
	v_mov_b32_e32 v7, v5
	s_nop 1
	v_permlane32_swap_b32_e32 v5, v7
	v_add_f32_e32 v12, v5, v7
	v_div_scale_f32 v13, s[6:7], v12, v12, 1.0
	v_rcp_f32_e32 v14, v13
	v_pk_mul_f32 v[4:5], v[66:67], v[4:5] op_sel_hi:[1,0]
	s_mov_b64 s[92:93], s[68:69]
	v_cvt_pk_bf16_f32 v79, v4, v5
	v_fma_f32 v4, -v13, v14, 1.0
	v_fmac_f32_e32 v14, v4, v14
	v_div_scale_f32 v4, vcc, 1.0, v12, 1.0
	v_mul_f32_e32 v5, v4, v14
	v_lshl_add_u64 v[106:107], v[10:11], 0, v[104:105]
	s_nop 1
	v_permlane16_swap_b32_e32 v76, v78
	v_permlane16_swap_b32_e32 v77, v79
	flat_store_dwordx4 v[106:107], v[76:79] offset:64
	v_fma_f32 v6, -v13, v5, v4
	v_fmac_f32_e32 v5, v6, v14
	v_lshlrev_b64 v[6:7], 11, v[90:91]
	v_fma_f32 v4, -v13, v5, v4
	v_lshl_add_u64 v[6:7], s[42:43], 0, v[6:7]
	v_div_fmas_f32 v4, v4, v14, v5
	v_lshl_add_u64 v[6:7], v[6:7], 0, s[44:45]
	v_div_fixup_f32 v4, v4, v12, 1.0
	v_lshl_add_u64 v[6:7], v[6:7], 0, v[8:9]
	v_lshl_add_u64 v[8:9], v[6:7], 0, s[8:9]
	v_pk_mul_f32 v[10:11], v[40:41], v[4:5] op_sel_hi:[1,0]
	v_pk_mul_f32 v[12:13], v[42:43], v[4:5] op_sel_hi:[1,0]
	v_add_co_u32_e32 v6, vcc, s2, v6
	v_cvt_pk_bf16_f32 v80, v10, v11
	v_cvt_pk_bf16_f32 v81, v12, v13
	v_addc_co_u32_e32 v7, vcc, 0, v7, vcc
	s_nop 0
	v_pk_mul_f32 v[6:7], v[36:37], v[4:5] op_sel_hi:[1,0]
	v_pk_mul_f32 v[10:11], v[38:39], v[4:5] op_sel_hi:[1,0]
	v_cvt_pk_bf16_f32 v82, v6, v7
	v_cvt_pk_bf16_f32 v83, v10, v11
	v_lshl_add_u64 v[106:107], v[8:9], 0, v[104:105]
	s_nop 1
	v_permlane16_swap_b32_e32 v80, v82
	v_permlane16_swap_b32_e32 v81, v83
	flat_store_dwordx4 v[106:107], v[80:83]
	v_pk_mul_f32 v[6:7], v[44:45], v[4:5] op_sel_hi:[1,0]
	v_pk_mul_f32 v[10:11], v[46:47], v[4:5] op_sel_hi:[1,0]
	v_cvt_pk_bf16_f32 v84, v6, v7
	v_cvt_pk_bf16_f32 v85, v10, v11
	s_nop 0
	v_pk_mul_f32 v[6:7], v[48:49], v[4:5] op_sel_hi:[1,0]
	v_pk_mul_f32 v[4:5], v[50:51], v[4:5] op_sel_hi:[1,0]
	v_cvt_pk_bf16_f32 v86, v6, v7
	v_cvt_pk_bf16_f32 v87, v4, v5
	v_lshl_add_u64 v[106:107], v[8:9], 0, v[104:105]
	s_nop 1
	v_permlane16_swap_b32_e32 v84, v86
	v_permlane16_swap_b32_e32 v85, v87
	flat_store_dwordx4 v[106:107], v[84:87] offset:64
	s_waitcnt lgkmcnt(0)
	s_barrier
	s_and_saveexec_b64 s[6:7], s[4:5]
	s_cbranch_execz .LBB0_1284
	s_cmp_eq_u32 s32, 0
	s_cbranch_scc1 .Lqf3
	s_waitcnt vmcnt(0) lgkmcnt(0)
	ds_write_b32 v178, v253
	s_mov_b32 s32, 0
	s_branch .LBB0_1284

.Lqe7:
	v_mov_b32_e32 v4, v101
	s_nop 1
	v_permlane16_swap_b32_e32 v101, v4
	v_add_f32_e32 v4, v101, v4
	v_mov_b32_e32 v5, v4
	s_nop 1
	v_permlane32_swap_b32_e32 v4, v5
	v_add_f32_e32 v4, v4, v5
	v_div_scale_f32 v5, s[6:7], v4, v4, 1.0
	v_rcp_f32_e32 v6, v5
	v_lshlrev_b32_e32 v88, 1, v97
	v_fma_f32 v7, -v5, v6, 1.0
	v_fmac_f32_e32 v6, v7, v6
	v_div_scale_f32 v7, vcc, 1.0, v4, 1.0
	v_mul_f32_e32 v8, v7, v6
	v_fma_f32 v9, -v5, v8, v7
	v_fmac_f32_e32 v8, v9, v6
	v_fma_f32 v5, -v5, v8, v7
	v_div_fmas_f32 v5, v5, v6, v8
	v_lshlrev_b64 v[6:7], 11, v[92:93]
	v_div_fixup_f32 v4, v5, v4, 1.0
	v_lshl_add_u64 v[6:7], s[48:49], 0, v[6:7]
	v_lshl_add_u64 v[6:7], v[6:7], 0, s[44:45]
	v_pk_mul_f32 v[8:9], v[68:69], v[4:5] op_sel_hi:[1,0]
	v_pk_mul_f32 v[10:11], v[70:71], v[4:5] op_sel_hi:[1,0]
	v_lshl_add_u64 v[6:7], v[6:7], 0, v[88:89]
	v_cvt_pk_bf16_f32 v16, v8, v9
	v_cvt_pk_bf16_f32 v17, v10, v11
	s_nop 0
	v_pk_mul_f32 v[8:9], v[64:65], v[4:5] op_sel_hi:[1,0]
	v_pk_mul_f32 v[10:11], v[66:67], v[4:5] op_sel_hi:[1,0]
	v_cvt_pk_bf16_f32 v18, v8, v9
	v_cvt_pk_bf16_f32 v19, v10, v11
	v_mbcnt_lo_u32_b32 v32, -1, 0
	v_mbcnt_hi_u32_b32 v32, -1, v32
	v_and_b32_e32 v32, 16, v32
	v_lshrrev_b32_e32 v32, 1, v32
	v_mul_u32_u24_e32 v32, 3, v32
	v_mov_b32_e32 v33, 0
	v_lshl_add_u64 v[34:35], v[6:7], 0, v[32:33]
	s_nop 1
	v_permlane16_swap_b32_e32 v16, v18
	v_permlane16_swap_b32_e32 v17, v19
	flat_store_dwordx4 v[34:35], v[16:19]
	v_pk_mul_f32 v[8:9], v[72:73], v[4:5] op_sel_hi:[1,0]
	v_pk_mul_f32 v[10:11], v[74:75], v[4:5] op_sel_hi:[1,0]
	v_cvt_pk_bf16_f32 v20, v8, v9
	v_cvt_pk_bf16_f32 v21, v10, v11
	s_nop 0
	v_pk_mul_f32 v[8:9], v[76:77], v[4:5] op_sel_hi:[1,0]
	v_mov_b32_e32 v5, v100
	s_nop 1
	v_permlane16_swap_b32_e32 v100, v5
	v_add_f32_e32 v5, v100, v5
	v_cvt_pk_bf16_f32 v22, v8, v9
	v_mov_b32_e32 v9, v5
	s_nop 1
	v_permlane32_swap_b32_e32 v5, v9
	v_add_f32_e32 v10, v5, v9
	v_div_scale_f32 v11, s[6:7], v10, v10, 1.0
	v_rcp_f32_e32 v12, v11
	v_pk_mul_f32 v[4:5], v[78:79], v[4:5] op_sel_hi:[1,0]
	s_nop 0
	v_cvt_pk_bf16_f32 v23, v4, v5
	v_fma_f32 v4, -v11, v12, 1.0
	v_fmac_f32_e32 v12, v4, v12
	v_div_scale_f32 v4, vcc, 1.0, v10, 1.0
	v_mul_f32_e32 v5, v4, v12
	v_lshl_add_u64 v[34:35], v[6:7], 0, v[32:33]
	s_nop 1
	v_permlane16_swap_b32_e32 v20, v22
	v_permlane16_swap_b32_e32 v21, v23
	flat_store_dwordx4 v[34:35], v[20:23] offset:64
	v_fma_f32 v6, -v11, v5, v4
	v_fmac_f32_e32 v5, v6, v12
	v_fma_f32 v4, -v11, v5, v4
	v_div_fmas_f32 v4, v4, v12, v5
	v_lshlrev_b64 v[6:7], 11, v[90:91]
	v_div_fixup_f32 v4, v4, v10, 1.0
	v_lshl_add_u64 v[6:7], s[48:49], 0, v[6:7]
	v_lshl_add_u64 v[6:7], v[6:7], 0, s[44:45]
	v_pk_mul_f32 v[8:9], v[52:53], v[4:5] op_sel_hi:[1,0]
	v_pk_mul_f32 v[10:11], v[54:55], v[4:5] op_sel_hi:[1,0]
	v_lshl_add_u64 v[6:7], v[6:7], 0, v[88:89]
	v_cvt_pk_bf16_f32 v24, v8, v9
	v_cvt_pk_bf16_f32 v25, v10, v11
	s_nop 0
	v_pk_mul_f32 v[8:9], v[48:49], v[4:5] op_sel_hi:[1,0]
	v_pk_mul_f32 v[10:11], v[50:51], v[4:5] op_sel_hi:[1,0]
	v_cvt_pk_bf16_f32 v26, v8, v9
	v_cvt_pk_bf16_f32 v27, v10, v11
	v_lshl_add_u64 v[34:35], v[6:7], 0, v[32:33]
	s_nop 1
	v_permlane16_swap_b32_e32 v24, v26
	v_permlane16_swap_b32_e32 v25, v27
	flat_store_dwordx4 v[34:35], v[24:27]
	v_pk_mul_f32 v[8:9], v[56:57], v[4:5] op_sel_hi:[1,0]
	v_pk_mul_f32 v[10:11], v[58:59], v[4:5] op_sel_hi:[1,0]
	v_cvt_pk_bf16_f32 v28, v8, v9
	v_cvt_pk_bf16_f32 v29, v10, v11
	s_nop 0
	v_pk_mul_f32 v[8:9], v[60:61], v[4:5] op_sel_hi:[1,0]
	v_pk_mul_f32 v[4:5], v[62:63], v[4:5] op_sel_hi:[1,0]
	v_cvt_pk_bf16_f32 v30, v8, v9
	v_cvt_pk_bf16_f32 v31, v4, v5
	v_lshl_add_u64 v[34:35], v[6:7], 0, v[32:33]
	s_nop 1
	v_permlane16_swap_b32_e32 v28, v30
	v_permlane16_swap_b32_e32 v29, v31
	flat_store_dwordx4 v[34:35], v[28:31] offset:64
	s_waitcnt lgkmcnt(0)
	s_barrier
	s_and_saveexec_b64 s[6:7], s[4:5]
	s_cbranch_execz .LBB0_2955
	s_cmp_eq_u32 s32, 0
	s_cbranch_scc1 .Lqf5
	s_waitcnt vmcnt(0) lgkmcnt(0)
	ds_write_b32 v177, v253
	s_mov_b32 s32, 0
	s_branch .LBB0_2955

.LBB0_3069:
	v_mov_b32_e32 v4, v97
	s_nop 1
	v_permlane16_swap_b32_e32 v97, v4
	v_add_f32_e32 v4, v97, v4
	v_mov_b32_e32 v5, v4
	s_nop 1
	v_permlane32_swap_b32_e32 v4, v5
	v_add_f32_e32 v4, v4, v5
	v_div_scale_f32 v5, s[6:7], v4, v4, 1.0
	v_rcp_f32_e32 v6, v5
	v_mov_b32_e32 v105, v89
	s_lshl_b32 s44, s78, 1
	s_mov_b64 s[76:77], s[66:67]
	v_fma_f32 v7, -v5, v6, 1.0
	v_fmac_f32_e32 v6, v7, v6
	v_div_scale_f32 v7, vcc, 1.0, v4, 1.0
	v_mul_f32_e32 v8, v7, v6
	v_fma_f32 v9, -v5, v8, v7
	v_fmac_f32_e32 v8, v9, v6
	v_fma_f32 v5, -v5, v8, v7
	v_div_fmas_f32 v5, v5, v6, v8
	v_lshlrev_b64 v[6:7], 11, v[92:93]
	v_lshl_add_u64 v[6:7], s[42:43], 0, v[6:7]
	v_lshl_add_u64 v[6:7], v[6:7], 0, s[44:45]
	v_lshlrev_b64 v[8:9], 1, v[104:105]
	v_div_fixup_f32 v4, v5, v4, 1.0
	v_lshl_add_u64 v[6:7], v[6:7], 0, v[8:9]
	v_lshl_add_u64 v[10:11], v[6:7], 0, s[96:97]
	v_pk_mul_f32 v[12:13], v[56:57], v[4:5] op_sel_hi:[1,0]
	v_pk_mul_f32 v[14:15], v[58:59], v[4:5] op_sel_hi:[1,0]
	v_add_co_u32_e32 v6, vcc, s94, v6
	v_cvt_pk_bf16_f32 v16, v12, v13
	v_cvt_pk_bf16_f32 v17, v14, v15
	v_addc_co_u32_e32 v7, vcc, 0, v7, vcc
	s_nop 0
	v_pk_mul_f32 v[6:7], v[52:53], v[4:5] op_sel_hi:[1,0]
	v_pk_mul_f32 v[12:13], v[54:55], v[4:5] op_sel_hi:[1,0]
	v_cvt_pk_bf16_f32 v18, v6, v7
	v_cvt_pk_bf16_f32 v19, v12, v13
	v_mbcnt_lo_u32_b32 v32, -1, 0
	v_mbcnt_hi_u32_b32 v32, -1, v32
	v_and_b32_e32 v32, 16, v32
	v_lshrrev_b32_e32 v32, 1, v32
	v_mul_u32_u24_e32 v32, 3, v32
	v_mov_b32_e32 v33, 0
	v_lshl_add_u64 v[34:35], v[10:11], 0, v[32:33]
	s_nop 1
	v_permlane16_swap_b32_e32 v16, v18
	v_permlane16_swap_b32_e32 v17, v19
	flat_store_dwordx4 v[34:35], v[16:19]
	v_pk_mul_f32 v[6:7], v[60:61], v[4:5] op_sel_hi:[1,0]
	v_pk_mul_f32 v[12:13], v[62:63], v[4:5] op_sel_hi:[1,0]
	v_cvt_pk_bf16_f32 v20, v6, v7
	v_cvt_pk_bf16_f32 v21, v12, v13
	s_nop 0
	v_pk_mul_f32 v[6:7], v[64:65], v[4:5] op_sel_hi:[1,0]
	v_mov_b32_e32 v5, v96
	s_nop 1
	v_permlane16_swap_b32_e32 v96, v5
	v_add_f32_e32 v5, v96, v5
	v_cvt_pk_bf16_f32 v22, v6, v7
	v_mov_b32_e32 v7, v5
	s_nop 1
	v_permlane32_swap_b32_e32 v5, v7
	v_add_f32_e32 v12, v5, v7
	v_div_scale_f32 v13, s[6:7], v12, v12, 1.0
	v_rcp_f32_e32 v14, v13
	v_pk_mul_f32 v[4:5], v[66:67], v[4:5] op_sel_hi:[1,0]
	s_nop 0
	v_cvt_pk_bf16_f32 v23, v4, v5
	v_fma_f32 v4, -v13, v14, 1.0
	v_fmac_f32_e32 v14, v4, v14
	v_div_scale_f32 v4, vcc, 1.0, v12, 1.0
	v_mul_f32_e32 v5, v4, v14
	v_lshl_add_u64 v[34:35], v[10:11], 0, v[32:33]
	s_nop 1
	v_permlane16_swap_b32_e32 v20, v22
	v_permlane16_swap_b32_e32 v21, v23
	flat_store_dwordx4 v[34:35], v[20:23] offset:64
	v_fma_f32 v6, -v13, v5, v4
	v_fmac_f32_e32 v5, v6, v14
	v_lshlrev_b64 v[6:7], 11, v[90:91]
	v_fma_f32 v4, -v13, v5, v4
	v_lshl_add_u64 v[6:7], s[42:43], 0, v[6:7]
	v_div_fmas_f32 v4, v4, v14, v5
	v_lshl_add_u64 v[6:7], v[6:7], 0, s[44:45]
	v_div_fixup_f32 v4, v4, v12, 1.0
	v_lshl_add_u64 v[6:7], v[6:7], 0, v[8:9]
	v_lshl_add_u64 v[8:9], v[6:7], 0, s[96:97]
	v_pk_mul_f32 v[10:11], v[40:41], v[4:5] op_sel_hi:[1,0]
	v_pk_mul_f32 v[12:13], v[42:43], v[4:5] op_sel_hi:[1,0]
	v_add_co_u32_e32 v6, vcc, s94, v6
	v_cvt_pk_bf16_f32 v24, v10, v11
	v_cvt_pk_bf16_f32 v25, v12, v13
	v_addc_co_u32_e32 v7, vcc, 0, v7, vcc
	s_nop 0
	v_pk_mul_f32 v[6:7], v[36:37], v[4:5] op_sel_hi:[1,0]
	v_pk_mul_f32 v[10:11], v[38:39], v[4:5] op_sel_hi:[1,0]
	v_cvt_pk_bf16_f32 v26, v6, v7
	v_cvt_pk_bf16_f32 v27, v10, v11
	v_lshl_add_u64 v[34:35], v[8:9], 0, v[32:33]
	s_nop 1
	v_permlane16_swap_b32_e32 v24, v26
	v_permlane16_swap_b32_e32 v25, v27
	flat_store_dwordx4 v[34:35], v[24:27]
	v_pk_mul_f32 v[6:7], v[44:45], v[4:5] op_sel_hi:[1,0]
	v_pk_mul_f32 v[10:11], v[46:47], v[4:5] op_sel_hi:[1,0]
	v_cvt_pk_bf16_f32 v28, v6, v7
	v_cvt_pk_bf16_f32 v29, v10, v11
	s_nop 0
	v_pk_mul_f32 v[6:7], v[48:49], v[4:5] op_sel_hi:[1,0]
	v_pk_mul_f32 v[4:5], v[50:51], v[4:5] op_sel_hi:[1,0]
	v_cvt_pk_bf16_f32 v30, v6, v7
	v_cvt_pk_bf16_f32 v31, v4, v5
	v_lshl_add_u64 v[34:35], v[8:9], 0, v[32:33]
	s_nop 1
	v_permlane16_swap_b32_e32 v28, v30
	v_permlane16_swap_b32_e32 v29, v31
	flat_store_dwordx4 v[34:35], v[28:31] offset:64
	s_waitcnt lgkmcnt(0)
	s_barrier
	s_and_saveexec_b64 s[6:7], s[4:5]
	s_cbranch_execz .LBB0_3041
	s_cmp_eq_u32 s32, 0
	s_cbranch_scc1 .Lqf8
	s_waitcnt vmcnt(0) lgkmcnt(0)
	ds_write_b32 v177, v253
	s_mov_b32 s32, 0
	s_branch .LBB0_3041
